# next-phase weight touch loads issued in each GEMM prologue after its first eight stage loads instead of at the phase header
# speedup vs baseline: 1.0157x; 1.0073x over previous
; __global__ void __launch_bounds__(512, 2) mega_fwd(Args args) {
;     ...
;             const int q = ph - 1, c = q / PH_PER_CHUNK, r = q - c * PH_PER_CHUNK;
;             const bool is_prompt = c < 2;
;             float* X = args.out + (size_t)c * TC * D;
;             const int L = is_prompt ? 2048 : 8192;
;             bf16_t* xb = (bf16_t*)(ws + ((c & 1) ? WS_XB : WS_X16));
;             {
;                 const int l = r / 9, k = r - l * 9;
;                 const bf16_t* WL = Wb + (size_t)l * W_LAYER_ELEMS;
;                 if (k == 0 || k == 7) {
.LBB0_18:
	v_readfirstlane_b32 s24, v196
	s_lshr_b32 s1, s24, 6
	v_readlane_b32 s0, v254, 6
	s_mov_b32 s21, s20
	s_add_i32 s0, s0, s1
	v_and_b32_e32 v170, 63, v196
	v_writelane_b32 v255, s1, 42
	s_cmp_lg_u32 s21, 0
	s_mov_b64 s[8:9], -1
	s_cbranch_scc0 .LBB0_422
	s_add_i32 s1, s21, -1
	s_mul_hi_i32 s4, s1, 0x38e38e39
	s_lshr_b32 s5, s4, 31
	s_ashr_i32 s4, s4, 2
	s_add_i32 s30, s4, s5
	s_mul_i32 s4, s30, 0xffffffee
	s_add_i32 s5, s4, s1
	s_bitcmp0_b32 s30, 0
	s_mov_b32 s1, 0x1d800000
	s_cselect_b32 s1, s1, 0x9e00000
	s_add_u32 s76, s80, s1
	s_mul_hi_i32 s1, s5, 0x38e38e39
	s_addc_u32 s77, s81, 0
	s_lshr_b32 s4, s1, 31
	s_ashr_i32 s12, s1, 1
	s_add_i32 s12, s12, s4
	s_mul_i32 s1, s12, -9
	v_writelane_b32 v255, s5, 43
	s_add_i32 s1, s1, s5
	s_mul_i32 s5, s12, 0x3180000
	s_mul_hi_i32 s4, s12, 0x3180000
	s_add_u32 s5, s80, s5
	v_writelane_b32 v255, s5, 44
	s_addc_u32 s4, s81, s4
	v_writelane_b32 v255, s4, 45
	s_mov_b32 s8, 0
	s_mov_b32 s9, 0
	s_cmp_eq_u32 s1, 0
	s_cselect_b32 s8, 0x580000, s8
	s_cselect_b32 s9, 0xb00000, s9
	s_cmp_eq_u32 s1, 1
	s_cselect_b32 s8, 0xb80000, s8
	s_cselect_b32 s9, 0x1080000, s9
	s_cmp_eq_u32 s1, 4
	s_cselect_b32 s8, 0x300000, s8
	s_cselect_b32 s9, 0x1c00000, s9
	s_cmp_eq_u32 s1, 5
	s_cselect_b32 s8, 0x200000, s8
	s_cselect_b32 s9, 0x1f00000, s9
	s_cmp_eq_u32 s1, 6
	s_cselect_b32 s8, 0xb00000, s8
	s_cselect_b32 s9, 0x2100000, s9
	s_cmp_eq_u32 s1, 7
	s_cselect_b32 s8, 0x580000, s8
	s_cselect_b32 s9, 0x2c00000, s9
	s_cmp_eq_u32 s1, 8
	s_cselect_b32 s8, 0xb00000, s8
	s_cselect_b32 s9, 0x3180000, s9
	s_cmp_eq_u32 s8, 0
	s_cbranch_scc1 .Lwpf_skip
	s_mov_b32 s100, s5
	s_mov_b32 s101, s4
	s_cmp_eq_u32 s1, 8
	s_cselect_b32 s38, s12, 0
	s_cmp_eq_u32 s38, 1
	s_cselect_b32 s100, s80, s100
	s_cselect_b32 s101, s81, s101
	s_cselect_b32 s9, 0, s9
	v_lshl_add_u32 v241, s0, 6, v170
	v_lshlrev_b32_e32 v241, 6, v241
	s_add_i32 s38, s8, -64
	v_min_u32_e32 v240, s38, v241
	v_add_u32_e32 v240, s9, v240
	v_add_u32_e32 v241, 0x800000, v241
	v_min_u32_e32 v241, s38, v241
	v_add_u32_e32 v241, s9, v241
	s_cmp_lg_u32 s1, 4
	s_cbranch_scc1 .Lwpf_skip
	s_lshr_b32 s8, s24, 6
	s_lshl_b32 s8, s8, 9
	s_add_i32 m0, s8, 0x20000
	s_nop 0
	global_load_lds_dword v240, s[100:101]
	s_add_i32 m0, s8, 0x20100
	s_nop 0
	global_load_lds_dword v241, s[100:101]

; #define PG8_STAGE(bufoff, gbase, voff) do { _Pragma("unroll") for (int _i = 0; _i < 2; ++_i) \
;         __builtin_amdgcn_global_load_lds((const unsigned*)((const char*)(gbase) + (voff)[_i]), (LAS unsigned*)(lds + (bufoff) + ldsw + _i * 8192), 16, 0, 0); } while (0)
; #define PG8_WAIT_V(n) asm volatile("s_waitcnt vmcnt(" #n ")" ::: "memory")
; #define PG8_BAR __builtin_amdgcn_s_barrier()
; template <class Epi>
; __device__ __forceinline__ void gemm_phase(LAS unsigned char* lds, const Gemm g, const Order& S, const Epi& E) {
;     ...
;     f32x4 acc[2][2][4][2];
; #pragma unroll
;     for (int a = 0; a < 2; ++a)
; #pragma unroll
;         for (int b = 0; b < 2; ++b)
; #pragma unroll
;             for (int m = 0; m < 4; ++m)
; #pragma unroll
;                 for (int n = 0; n < 2; ++n) acc[a][b][m][n] = (f32x4){0.f, 0.f, 0.f, 0.f};
;     bf16x8 At[4][2], B0[2][2], B1[2][2];
;     const char* cA = (const char*)(g.A + (size_t)cur.pm * BM * g.lda + (size_t)cur.z * g.za);
;     const char* cB = (const char*)(g.Bt + (size_t)cur.pn * BM * g.ldb + (size_t)cur.z * g.zb);
;     constexpr bool ALIGN_EPI = Epi::ALIGN && !Epi::AFTER_DRAIN;
;     PG8_STAGE(PG8_SB(0, 0), cB, voffB); PG8_STAGE(PG8_SB(0, 1), cB + hstepB, voffB); PG8_STAGE(PG8_SA(0, 0), cA, voffA); PG8_STAGE(PG8_SA(0, 1), cA + hstepA, voffA);
;     if (wr == 1) PG8_BAR;
;     PG8_WAIT_V(2); PG8_BAR;
;     PG8_STAGE(PG8_SB(1, 0), cB + kstep, voffB); PG8_STAGE(PG8_SA(1, 0), cA + kstep, voffA); PG8_STAGE(PG8_SB(1, 1), cB + hstepB + kstep, voffB);
;     PG8_WAIT_V(6); PG8_BAR;
.LBB0_159:
	s_lshr_b32 m0, s67, 1
	s_add_i32 m0, m0, 0x20000
	s_nop 0
	global_load_lds_dword v240, s[100:101]
	s_add_i32 m0, m0, 0x100
	s_nop 0
	global_load_lds_dword v241, s[100:101]
	v_lshl_add_u64 v[6:7], s[68:69], 0, v[160:161]
	v_mov_b32_e32 v129, v161
	v_lshl_add_u64 v[8:9], s[68:69], 0, v[128:129]
	v_mov_b32_e32 v133, v161
	s_add_i32 m0, s67, 0x18000
	v_lshl_add_u64 v[6:7], v[6:7], 0, s[62:63]
	v_lshl_add_u64 v[14:15], s[70:71], 0, v[132:133]
	v_mov_b32_e32 v131, v161
	s_waitcnt vmcnt(2)
	s_barrier
	global_load_lds_dwordx4 v[6:7], off
	v_lshl_add_u64 v[6:7], v[8:9], 0, s[62:63]
	s_add_i32 m0, s67, 0x1a000
	s_add_i32 s50, s67, 0x8000
	v_lshl_add_u64 v[16:17], s[70:71], 0, v[130:131]
	global_load_lds_dwordx4 v[6:7], off
	v_lshl_add_u64 v[6:7], v[14:15], 0, s[62:63]
	s_mov_b32 m0, s50
	s_add_i32 s51, s67, 0xa000
	v_lshl_add_u64 v[10:11], s[40:41], 0, v[160:161]
	global_load_lds_dwordx4 v[6:7], off
	v_lshl_add_u64 v[6:7], v[16:17], 0, s[62:63]
	s_mov_b32 m0, s51
	v_lshl_add_u64 v[12:13], s[40:41], 0, v[128:129]
	global_load_lds_dwordx4 v[6:7], off
	s_add_i32 m0, s67, 0x1c000
	v_lshl_add_u64 v[6:7], v[10:11], 0, s[62:63]
	global_load_lds_dwordx4 v[6:7], off
	v_lshl_add_u64 v[6:7], v[12:13], 0, s[62:63]
	s_add_i32 m0, s67, 0x1e000
	v_and_b32_e32 v142, 15, v145
	global_load_lds_dwordx4 v[6:7], off
	v_and_b32_e32 v18, 48, v145
	v_lshlrev_b32_e32 v19, 2, v145
	s_and_b32 s24, s22, 3
	s_lshr_b32 s8, s8, 6
	s_lshl_b32 s4, s9, 13
	v_lshl_or_b32 v18, v142, 6, v18
	v_and_b32_e32 v19, 32, v19
	s_lshl_b32 s48, s9, 6
	v_bitop3_b32 v20, v18, s4, v19 bitop3:0xde
	s_lshl_b32 s4, s24, 12
	s_add_i32 s49, s8, -2
	s_waitcnt vmcnt(6)
	s_add_u32 s30, s28, 0x80
	v_add_u32_e32 v3, v5, v3
	v_add_u32_e32 v0, v2, v0
	v_bitop3_b32 v143, v18, s4, v19 bitop3:0xde
	s_addc_u32 s31, 0, 0
	v_add_lshl_u32 v4, v3, v4, 1
	v_mov_b32_e32 v5, v161
	v_add_lshl_u32 v0, v0, v1, 1
	v_mov_b32_e32 v1, v161
	v_mov_b32_e32 v32, 0
	v_readlane_b32 s4, v254, 9
	v_writelane_b32 v255, s22, 58
	v_or_b32_e32 v171, s48, v142
	v_lshl_add_u64 v[134:135], s[30:31], 0, v[4:5]
	v_lshl_add_u64 v[136:137], s[30:31], 0, v[0:1]
	s_mov_b32 s34, 0
	v_add_u32_e32 v144, 0, v20
	s_mov_b32 s66, s4
	v_readlane_b32 s9, v254, 33
	v_mov_b32_e32 v33, v32
	v_mov_b32_e32 v34, v32
	v_mov_b32_e32 v35, v32
	v_mov_b32_e32 v36, v32
	v_mov_b32_e32 v37, v32
	v_mov_b32_e32 v38, v32
	v_mov_b32_e32 v39, v32
	v_mov_b32_e32 v40, v32
	v_mov_b32_e32 v41, v32
	v_mov_b32_e32 v42, v32
	v_mov_b32_e32 v43, v32
	v_mov_b32_e32 v44, v32
	v_mov_b32_e32 v45, v32
	v_mov_b32_e32 v46, v32
	v_mov_b32_e32 v47, v32
	v_mov_b32_e32 v96, v32
	v_mov_b32_e32 v97, v32
	v_mov_b32_e32 v98, v32
	v_mov_b32_e32 v99, v32
	v_mov_b32_e32 v100, v32
	v_mov_b32_e32 v101, v32
	v_mov_b32_e32 v102, v32
	v_mov_b32_e32 v103, v32
	s_waitcnt vmcnt(0)
	v_mov_b32_e32 v104, v32
	v_mov_b32_e32 v105, v32
	v_mov_b32_e32 v106, v32
	v_mov_b32_e32 v107, v32
	v_mov_b32_e32 v108, v32
	v_mov_b32_e32 v109, v32
	v_mov_b32_e32 v110, v32
	v_mov_b32_e32 v111, v32
	v_mov_b32_e32 v48, v32
	v_mov_b32_e32 v49, v32
	v_mov_b32_e32 v50, v32
	v_mov_b32_e32 v51, v32
	v_mov_b32_e32 v52, v32
	v_mov_b32_e32 v53, v32
	v_mov_b32_e32 v54, v32
	v_mov_b32_e32 v55, v32
	v_mov_b32_e32 v56, v32
	v_mov_b32_e32 v57, v32
	v_mov_b32_e32 v58, v32
	v_mov_b32_e32 v59, v32
	v_mov_b32_e32 v60, v32
	v_mov_b32_e32 v61, v32
	v_mov_b32_e32 v62, v32
	v_mov_b32_e32 v63, v32
	v_mov_b32_e32 v112, v32
	v_mov_b32_e32 v113, v32
	v_mov_b32_e32 v114, v32
	v_mov_b32_e32 v115, v32
	v_mov_b32_e32 v116, v32
	v_mov_b32_e32 v117, v32
	v_mov_b32_e32 v118, v32
	v_mov_b32_e32 v119, v32
	v_mov_b32_e32 v120, v32
	v_mov_b32_e32 v121, v32
	v_mov_b32_e32 v122, v32
	v_mov_b32_e32 v123, v32
	v_mov_b32_e32 v124, v32
	v_mov_b32_e32 v125, v32
	v_mov_b32_e32 v126, v32
	v_mov_b32_e32 v127, v32
	v_mov_b32_e32 v80, v32
	v_mov_b32_e32 v81, v32
	v_mov_b32_e32 v82, v32
	v_mov_b32_e32 v83, v32
	v_mov_b32_e32 v84, v32
	v_mov_b32_e32 v85, v32
	v_mov_b32_e32 v86, v32
	v_mov_b32_e32 v87, v32
	v_mov_b32_e32 v64, v32
	v_mov_b32_e32 v65, v32
	v_mov_b32_e32 v66, v32
	v_mov_b32_e32 v67, v32
	v_mov_b32_e32 v68, v32
	v_mov_b32_e32 v69, v32
	v_mov_b32_e32 v70, v32
	v_mov_b32_e32 v71, v32
	v_mov_b32_e32 v0, v32
	v_mov_b32_e32 v1, v32
	v_mov_b32_e32 v2, v32
	v_mov_b32_e32 v3, v32
	v_mov_b32_e32 v4, v32
	v_mov_b32_e32 v5, v32
	v_mov_b32_e32 v6, v32
	v_mov_b32_e32 v7, v32
	v_mov_b32_e32 v8, v32
	v_mov_b32_e32 v9, v32
	v_mov_b32_e32 v10, v32
	v_mov_b32_e32 v11, v32
	v_mov_b32_e32 v12, v32
	v_mov_b32_e32 v13, v32
	v_mov_b32_e32 v14, v32
	v_mov_b32_e32 v15, v32
	v_mov_b32_e32 v88, v32
	v_mov_b32_e32 v89, v32
	v_mov_b32_e32 v90, v32
	v_mov_b32_e32 v91, v32
	v_mov_b32_e32 v92, v32
	v_mov_b32_e32 v93, v32
	v_mov_b32_e32 v94, v32
	v_mov_b32_e32 v95, v32
	v_mov_b32_e32 v72, v32
	v_mov_b32_e32 v73, v32
	v_mov_b32_e32 v74, v32
	v_mov_b32_e32 v75, v32
	v_mov_b32_e32 v76, v32
	v_mov_b32_e32 v77, v32
	v_mov_b32_e32 v78, v32
	v_mov_b32_e32 v79, v32
	v_mov_b32_e32 v16, v32
	v_mov_b32_e32 v17, v32
	v_mov_b32_e32 v18, v32
	v_mov_b32_e32 v19, v32
	v_mov_b32_e32 v20, v32
	v_mov_b32_e32 v21, v32
	v_mov_b32_e32 v22, v32
	v_mov_b32_e32 v23, v32
	v_mov_b32_e32 v24, v32
	v_mov_b32_e32 v25, v32
	v_mov_b32_e32 v26, v32
	v_mov_b32_e32 v27, v32
	v_mov_b32_e32 v28, v32
	v_mov_b32_e32 v29, v32
	v_mov_b32_e32 v30, v32
	v_mov_b32_e32 v31, v32
	s_barrier
	s_branch .LBB0_161

; #define PG8_STAGE(bufoff, gbase, voff) do { _Pragma("unroll") for (int _i = 0; _i < 2; ++_i) \
;         __builtin_amdgcn_global_load_lds((const unsigned*)((const char*)(gbase) + (voff)[_i]), (LAS unsigned*)(lds + (bufoff) + ldsw + _i * 8192), 16, 0, 0); } while (0)
; #define PG8_WAIT_V(n) asm volatile("s_waitcnt vmcnt(" #n ")" ::: "memory")
; #define PG8_BAR __builtin_amdgcn_s_barrier()
; template <class Epi>
; __device__ __forceinline__ void gemm_phase(LAS unsigned char* lds, const Gemm g, const Order& S, const Epi& E) {
;     ...
;     f32x4 acc[2][2][4][2];
; #pragma unroll
;     for (int a = 0; a < 2; ++a)
; #pragma unroll
;         for (int b = 0; b < 2; ++b)
; #pragma unroll
;             for (int m = 0; m < 4; ++m)
; #pragma unroll
;                 for (int n = 0; n < 2; ++n) acc[a][b][m][n] = (f32x4){0.f, 0.f, 0.f, 0.f};
;     bf16x8 At[4][2], B0[2][2], B1[2][2];
;     const char* cA = (const char*)(g.A + (size_t)cur.pm * BM * g.lda + (size_t)cur.z * g.za);
;     const char* cB = (const char*)(g.Bt + (size_t)cur.pn * BM * g.ldb + (size_t)cur.z * g.zb);
;     constexpr bool ALIGN_EPI = Epi::ALIGN && !Epi::AFTER_DRAIN;
;     PG8_STAGE(PG8_SB(0, 0), cB, voffB); PG8_STAGE(PG8_SB(0, 1), cB + hstepB, voffB); PG8_STAGE(PG8_SA(0, 0), cA, voffA); PG8_STAGE(PG8_SA(0, 1), cA + hstepA, voffA);
;     if (wr == 1) PG8_BAR;
;     PG8_WAIT_V(2); PG8_BAR;
;     PG8_STAGE(PG8_SB(1, 0), cB + kstep, voffB); PG8_STAGE(PG8_SA(1, 0), cA + kstep, voffA); PG8_STAGE(PG8_SB(1, 1), cB + hstepB + kstep, voffB);
;     PG8_WAIT_V(6); PG8_BAR;
.LBB0_267:
	s_lshr_b32 m0, s25, 1
	s_add_i32 m0, m0, 0x20000
	s_nop 0
	global_load_lds_dword v240, s[100:101]
	s_add_i32 m0, m0, 0x100
	s_nop 0
	global_load_lds_dword v241, s[100:101]
	v_lshrrev_b32_e32 v18, 1, v8
	v_and_b32_e32 v18, 24, v18
	v_and_b32_e32 v13, 15, v8
	v_lshlrev_b32_e32 v19, 1, v18
	v_lshlrev_b32_e32 v8, 2, v8
	v_lshl_or_b32 v171, s29, 6, v13
	v_lshl_or_b32 v13, v13, 6, v19
	s_lshl_b32 s4, s29, 13
	v_and_b32_e32 v8, 32, v8
	v_readlane_b32 s64, v254, 43
	v_bitop3_b32 v19, v13, s4, v8 bitop3:0xde
	s_lshl_b32 s4, s13, 5
	v_mov_b32_e32 v133, v161
	v_readlane_b32 s65, v254, 44
	s_and_b32 s6, s4, 0x60
	s_add_i32 m0, s25, 0x18000
	v_lshl_add_u64 v[0:1], v[0:1], 0, s[62:63]
	v_lshl_add_u64 v[14:15], s[64:65], 0, v[132:133]
	v_mov_b32_e32 v131, v161
	s_lshl_b32 s4, s6, 7
	s_waitcnt vmcnt(2)
	s_barrier
	global_load_lds_dwordx4 v[0:1], off
	v_lshl_add_u64 v[0:1], v[2:3], 0, s[62:63]
	s_add_i32 m0, s25, 0x1a000
	s_add_i32 s29, s25, 0x8000
	s_add_i32 s70, s25, 0xa000
	v_lshl_add_u64 v[16:17], s[64:65], 0, v[130:131]
	v_bitop3_b32 v184, v13, s4, v8 bitop3:0xde
	global_load_lds_dwordx4 v[0:1], off
	v_lshl_add_u64 v[0:1], v[14:15], 0, s[62:63]
	s_mov_b32 m0, s29
	s_add_u32 s4, s66, 0x20080
	global_load_lds_dwordx4 v[0:1], off
	v_lshl_add_u64 v[0:1], v[16:17], 0, s[62:63]
	s_mov_b32 m0, s70
	s_addc_u32 s5, s67, 0
	global_load_lds_dwordx4 v[0:1], off
	s_add_i32 m0, s25, 0x1c000
	v_lshl_add_u64 v[0:1], s[4:5], 0, v[160:161]
	global_load_lds_dwordx4 v[0:1], off
	v_lshl_add_u64 v[0:1], s[4:5], 0, v[128:129]
	s_add_i32 m0, s25, 0x1e000
	v_or_b32_e32 v185, s6, v18
	global_load_lds_dwordx4 v[0:1], off
	s_movk_i32 s6, 0x600
	v_lshrrev_b32_e32 v1, 1, v10
	v_mul_lo_u32 v0, v9, s6
	s_movk_i32 s7, 0x6000
	v_mad_u64_u32 v[0:1], s[4:5], v1, s7, v[0:1]
	v_or_b32_e32 v0, v0, v11
	v_add_lshl_u32 v0, v0, v12, 1
	v_mov_b32_e32 v1, v161
	s_mov_b64 s[30:31], 0x60080
	v_lshl_add_u64 v[134:135], v[0:1], 0, s[30:31]
	v_lshrrev_b32_e32 v1, 1, v4
	v_mul_lo_u32 v0, v5, s6
	v_mad_u64_u32 v[0:1], s[4:5], v1, s7, v[0:1]
	v_or_b32_e32 v0, v0, v6
	s_waitcnt vmcnt(6)
	v_add_lshl_u32 v0, v0, v7, 1
	v_mov_b32_e32 v1, v161
	s_cmpk_lt_u32 s12, 0x100
	v_lshl_add_u64 v[136:137], v[0:1], 0, s[30:31]
	v_mov_b32_e32 v0, 0
	s_cselect_b64 s[12:13], -1, 0
	s_mov_b32 s42, 0
	v_add_u32_e32 v186, 0, v19
	v_readlane_b32 s30, v254, 9
	v_readlane_b32 s31, v254, 33
	s_mov_b32 s71, 0
	v_mov_b32_e32 v1, v0
	v_mov_b32_e32 v2, v0
	v_mov_b32_e32 v3, v0
	v_mov_b32_e32 v4, v0
	v_mov_b32_e32 v5, v0
	v_mov_b32_e32 v6, v0
	v_mov_b32_e32 v7, v0
	v_mov_b32_e32 v8, v0
	v_mov_b32_e32 v9, v0
	v_mov_b32_e32 v10, v0
	v_mov_b32_e32 v11, v0
	v_mov_b32_e32 v12, v0
	v_mov_b32_e32 v13, v0
	v_mov_b32_e32 v14, v0
	v_mov_b32_e32 v15, v0
	v_mov_b32_e32 v16, v0
	v_mov_b32_e32 v17, v0
	v_mov_b32_e32 v18, v0
	v_mov_b32_e32 v19, v0
	v_mov_b32_e32 v20, v0
	v_mov_b32_e32 v21, v0
	v_mov_b32_e32 v22, v0
	v_mov_b32_e32 v23, v0
	v_mov_b32_e32 v24, v0
	v_mov_b32_e32 v25, v0
	v_mov_b32_e32 v26, v0
	v_mov_b32_e32 v27, v0
	v_mov_b32_e32 v28, v0
	v_mov_b32_e32 v29, v0
	v_mov_b32_e32 v30, v0
	v_mov_b32_e32 v31, v0
	v_mov_b32_e32 v32, v0
	v_mov_b32_e32 v33, v0
	v_mov_b32_e32 v34, v0
	v_mov_b32_e32 v35, v0
	v_mov_b32_e32 v36, v0
	v_mov_b32_e32 v37, v0
	v_mov_b32_e32 v38, v0
	v_mov_b32_e32 v39, v0
	v_mov_b32_e32 v40, v0
	v_mov_b32_e32 v41, v0
	v_mov_b32_e32 v42, v0
	v_mov_b32_e32 v43, v0
	v_mov_b32_e32 v44, v0
	v_mov_b32_e32 v45, v0
	v_mov_b32_e32 v46, v0
	v_mov_b32_e32 v47, v0
	v_mov_b32_e32 v48, v0
	v_mov_b32_e32 v49, v0
	v_mov_b32_e32 v50, v0
	v_mov_b32_e32 v51, v0
	v_mov_b32_e32 v52, v0
	v_mov_b32_e32 v53, v0
	v_mov_b32_e32 v54, v0
	v_mov_b32_e32 v55, v0
	v_mov_b32_e32 v56, v0
	v_mov_b32_e32 v57, v0
	v_mov_b32_e32 v58, v0
	v_mov_b32_e32 v59, v0
	v_mov_b32_e32 v60, v0
	v_mov_b32_e32 v61, v0
	v_mov_b32_e32 v62, v0
	v_mov_b32_e32 v63, v0
	v_mov_b32_e32 v64, v0
	v_mov_b32_e32 v65, v0
	v_mov_b32_e32 v66, v0
	v_mov_b32_e32 v67, v0
	v_mov_b32_e32 v68, v0
	v_mov_b32_e32 v69, v0
	v_mov_b32_e32 v70, v0
	v_mov_b32_e32 v71, v0
	v_mov_b32_e32 v72, v0
	v_mov_b32_e32 v73, v0
	v_mov_b32_e32 v74, v0
	v_mov_b32_e32 v75, v0
	v_mov_b32_e32 v76, v0
	v_mov_b32_e32 v77, v0
	v_mov_b32_e32 v78, v0
	v_mov_b32_e32 v79, v0
	v_mov_b32_e32 v80, v0
	v_mov_b32_e32 v81, v0
	v_mov_b32_e32 v82, v0
	v_mov_b32_e32 v83, v0
	s_waitcnt vmcnt(0)
	v_mov_b32_e32 v84, v0
	v_mov_b32_e32 v85, v0
	v_mov_b32_e32 v86, v0
	v_mov_b32_e32 v87, v0
	v_mov_b32_e32 v88, v0
	v_mov_b32_e32 v89, v0
	v_mov_b32_e32 v90, v0
	v_mov_b32_e32 v91, v0
	v_mov_b32_e32 v92, v0
	v_mov_b32_e32 v93, v0
	v_mov_b32_e32 v94, v0
	v_mov_b32_e32 v95, v0
	v_mov_b32_e32 v96, v0
	v_mov_b32_e32 v97, v0
	v_mov_b32_e32 v98, v0
	v_mov_b32_e32 v99, v0
	v_mov_b32_e32 v100, v0
	v_mov_b32_e32 v101, v0
	v_mov_b32_e32 v102, v0
	v_mov_b32_e32 v103, v0
	v_mov_b32_e32 v104, v0
	v_mov_b32_e32 v105, v0
	v_mov_b32_e32 v106, v0
	v_mov_b32_e32 v107, v0
	v_mov_b32_e32 v108, v0
	v_mov_b32_e32 v109, v0
	v_mov_b32_e32 v110, v0
	v_mov_b32_e32 v111, v0
	v_mov_b32_e32 v112, v0
	v_mov_b32_e32 v113, v0
	v_mov_b32_e32 v114, v0
	v_mov_b32_e32 v115, v0
	v_mov_b32_e32 v116, v0
	v_mov_b32_e32 v117, v0
	v_mov_b32_e32 v118, v0
	v_mov_b32_e32 v119, v0
	v_mov_b32_e32 v120, v0
	v_mov_b32_e32 v121, v0
	v_mov_b32_e32 v122, v0
	v_mov_b32_e32 v123, v0
	v_mov_b32_e32 v124, v0
	v_mov_b32_e32 v125, v0
	v_mov_b32_e32 v126, v0
	v_mov_b32_e32 v127, v0
	s_barrier
	s_branch .LBB0_270

; #define PG8_STAGE(bufoff, gbase, voff) do { _Pragma("unroll") for (int _i = 0; _i < 2; ++_i) \
;         __builtin_amdgcn_global_load_lds((const unsigned*)((const char*)(gbase) + (voff)[_i]), (LAS unsigned*)(lds + (bufoff) + ldsw + _i * 8192), 16, 0, 0); } while (0)
; #define PG8_WAIT_V(n) asm volatile("s_waitcnt vmcnt(" #n ")" ::: "memory")
; #define PG8_BAR __builtin_amdgcn_s_barrier()
; template <class Epi>
; __device__ __forceinline__ void gemm_phase(LAS unsigned char* lds, const Gemm g, const Order& S, const Epi& E) {
;     ...
;     PG8_STAGE(PG8_SB(0, 0), cB, voffB); PG8_STAGE(PG8_SB(0, 1), cB + hstepB, voffB); PG8_STAGE(PG8_SA(0, 0), cA, voffA); PG8_STAGE(PG8_SA(0, 1), cA + hstepA, voffA);
;     if (wr == 1) PG8_BAR;
;     PG8_WAIT_V(2); PG8_BAR;
;     PG8_STAGE(PG8_SB(1, 0), cB + kstep, voffB); PG8_STAGE(PG8_SA(1, 0), cA + kstep, voffA); PG8_STAGE(PG8_SB(1, 1), cB + hstepB + kstep, voffB);
;     PG8_WAIT_V(6); PG8_BAR;
.LBB0_390:
	s_lshr_b32 m0, s24, 1
	s_add_i32 m0, m0, 0x20000
	s_nop 0
	global_load_lds_dword v240, s[100:101]
	s_add_i32 m0, m0, 0x100
	s_nop 0
	global_load_lds_dword v241, s[100:101]
	v_lshl_add_u64 v[8:9], s[64:65], 0, v[160:161]
	v_mov_b32_e32 v129, v161
	s_lshl_b32 s5, s28, 5
	v_lshl_add_u64 v[10:11], s[64:65], 0, v[128:129]
	v_mov_b32_e32 v133, v161
	s_and_b32 s5, s5, 0x60
	s_add_i32 m0, s24, 0x18000
	v_lshl_add_u64 v[8:9], v[8:9], 0, s[62:63]
	v_lshl_add_u64 v[12:13], s[50:51], 0, v[132:133]
	v_mov_b32_e32 v131, v161
	s_lshl_b32 s4, s31, 13
	s_lshl_b32 s36, s5, 7
	s_waitcnt vmcnt(2)
	s_barrier
	global_load_lds_dwordx4 v[8:9], off
	v_lshl_add_u64 v[8:9], v[10:11], 0, s[62:63]
	s_add_i32 m0, s24, 0x1a000
	s_add_i32 s28, s24, 0x8000
	s_add_i32 s29, s24, 0xa000
	v_lshl_add_u64 v[14:15], s[50:51], 0, v[130:131]
	global_load_lds_dwordx4 v[8:9], off
	v_lshl_add_u64 v[8:9], v[12:13], 0, s[62:63]
	s_mov_b32 m0, s28
	s_add_u32 s34, s64, 0x40080
	global_load_lds_dwordx4 v[8:9], off
	v_lshl_add_u64 v[8:9], v[14:15], 0, s[62:63]
	s_mov_b32 m0, s29
	s_addc_u32 s35, s65, 0
	global_load_lds_dwordx4 v[8:9], off
	s_add_i32 m0, s24, 0x1c000
	v_lshl_add_u64 v[8:9], s[34:35], 0, v[160:161]
	global_load_lds_dwordx4 v[8:9], off
	v_lshl_add_u64 v[8:9], s[34:35], 0, v[128:129]
	s_add_i32 m0, s24, 0x1e000
	v_and_b32_e32 v7, 15, v0
	global_load_lds_dwordx4 v[8:9], off
	v_lshrrev_b32_e32 v8, 1, v0
	v_and_b32_e32 v8, 24, v8
	v_lshlrev_b32_e32 v9, 1, v8
	v_lshlrev_b32_e32 v0, 2, v0
	v_lshl_or_b32 v140, s31, 6, v7
	v_lshl_or_b32 v7, v7, 6, v9
	v_and_b32_e32 v0, 32, v0
	v_bitop3_b32 v9, v7, s4, v0 bitop3:0xde
	v_bitop3_b32 v141, v7, s36, v0 bitop3:0xde
	v_lshlrev_b32_e32 v0, 14, v5
	v_and_b32_e32 v0, 0xffff8000, v0
	v_lshl_add_u32 v0, v4, 11, v0
	v_and_b32_e32 v4, 1, v5
	v_lshl_or_b32 v0, v4, 6, v0
	v_lshl_add_u32 v134, v6, 1, v0
	v_lshlrev_b32_e32 v0, 14, v1
	v_and_b32_e32 v0, 0xffff8000, v0
	s_waitcnt vmcnt(6)
	v_lshl_add_u32 v0, v2, 11, v0
	v_and_b32_e32 v1, 1, v1
	s_cmpk_lt_u32 s30, 0x100
	v_or_b32_e32 v142, s5, v8
	v_lshl_or_b32 v0, v1, 6, v0
	v_readlane_b32 s4, v254, 15
	s_cselect_b64 s[40:41], -1, 0
	v_mov_b32_e32 v135, v161
	v_lshl_add_u32 v136, v3, 1, v0
	v_mov_b32_e32 v137, v161
	s_mov_b32 s68, 0
	v_add_u32_e32 v143, 0, v9
	v_readlane_b32 s30, v254, 10
	s_mov_b32 s31, s4
	s_barrier
	v_readlane_b32 s5, v254, 16
	s_waitcnt vmcnt(0)
	s_branch .LBB0_393
